# best_v22 plus half-barrier K-loop (per-half loop copies, lead keeps pre-MFMA barriers, trail post-MFMA) in the FFN-up GEMM only
# speedup vs baseline: 1.0083x; 1.0083x over previous
; #define PG8_STAGE(bufoff, gbase, voff) do { _Pragma("unroll") for (int _i = 0; _i < 2; ++_i) \
;         __builtin_amdgcn_global_load_lds((const unsigned*)((const char*)(gbase) + (voff)[_i]), (PG8_LAS unsigned*)(lds + (bufoff) + ldsw + _i * 8192), 16, 0, 0); } while (0)
; #define PG8_LDA(dst, b, h) do { _Pragma("unroll") for (int m = 0; m < 4; ++m) _Pragma("unroll") for (int k = 0; k < 2; ++k) dst[m][k] = *(const PG8_LAS bf16x8*)(lds + PG8_SA(b, h) + aoff + m * 2048 + k * 1024); } while (0)
; #define PG8_LDB(dst, b, h) do { _Pragma("unroll") for (int n = 0; n < 2; ++n) _Pragma("unroll") for (int k = 0; k < 2; ++k) dst[n][k] = *(const PG8_LAS bf16x8*)(lds + PG8_SB(b, h) + boff + n * 2048 + k * 1024); } while (0)
; #define PG8_MMA(ai, bj, At, Bt) do { __builtin_amdgcn_s_setprio(1); _Pragma("unroll") for (int m = 0; m < 4; ++m) _Pragma("unroll") for (int n = 0; n < 2; ++n) _Pragma("unroll") for (int k = 0; k < 2; ++k) \
;         acc[ai][bj][m][n] = __builtin_amdgcn_mfma_f32_16x16x32_bf16(Bt[n][k], At[m][k], acc[ai][bj][m][n], 0, 0, 0); __builtin_amdgcn_s_setprio(0); } while (0)
; #define PG8_WAIT_V(n) asm volatile("s_waitcnt vmcnt(" #n ")" ::: "memory")
; #define PG8_WAIT_L(n) asm volatile("s_waitcnt lgkmcnt(" #n ")" ::: "memory")
; template <class Epi, class Sched, bool ALIGN_EPI = false, bool SP2 = false>
; __device__ __forceinline__ void gemm_phase(PG8_LAS unsigned char* lds, const Gemm g, const Sched& S, const Epi& E) {
;     ...
;             const bool last = (t == nt - 2);
;             const char* a1 = cA + (size_t)(t + 1) * kstep;
;             const char* a2 = last ? nA : cA + (size_t)(t + 2) * kstep; const char* b2 = last ? nB : cB + (size_t)(t + 2) * kstep;
;             const char* a3 = a2 + kstep; const char* b3 = b2 + kstep;
;             if (last && has_next) S.a_ready(nxt);
;             if constexpr (SP2) {
;             PG8_LDB(B0, 0, 0); PG8_LDB(B1, 0, 1); PG8_SCHED; PG8_LDA(At, 0, 0); PG8_STAGE(PG8_SA(1, 1), a1 + hstep, voffA);
;             PG8_WAIT_V(8); PG8_WAIT_L(0); PG8_BAR; PG8_MMA(0, 0, At, B0); PG8_MMA(0, 1, At, B1); PG8_BAR; PG8_SCHED;
;             PG8_LDA(At, 0, 1); PG8_STAGE(PG8_SB(0, 0), b2, voffB); PG8_STAGE(PG8_SB(0, 1), b2 + hstep, voffB); PG8_STAGE(PG8_SA(0, 0), a2, voffA);
;             PG8_WAIT_V(8); PG8_WAIT_L(0); PG8_BAR; PG8_MMA(1, 0, At, B0); PG8_MMA(1, 1, At, B1); PG8_BAR; PG8_SCHED;
.Lk0_lead:
	s_add_u32 s20, s18, 0x4000
	s_addc_u32 s21, s19, 0
	s_cmp_eq_u32 s68, 12
	s_cselect_b32 s64, s40, s20
	s_cselect_b32 s65, s11, s21
	s_cselect_b32 s62, s61, s66
	s_cselect_b32 s63, s9, s67
	s_add_u32 s20, s64, 0x8000
	s_addc_u32 s21, s65, 0
	s_add_i32 s69, 0, 0x10000
	s_add_i32 s72, 0, 0x14000
	v_add_u32_e32 v140, s69, v162
	v_add_u32_e32 v160, s72, v162
	ds_read_b128 v[128:131], v140
	ds_read_b128 v[132:135], v140 offset:1024
	ds_read_b128 v[136:139], v140 offset:2048
	ds_read_b128 v[140:143], v140 offset:3072
	ds_read_b128 v[156:159], v160
	ds_read_b128 v[164:167], v160 offset:1024
	ds_read_b128 v[168:171], v160 offset:2048
	ds_read_b128 v[172:175], v160 offset:3072
	s_add_i32 m0, s37, 0xc000
	ds_read_b128 v[176:179], v163
	ds_read_b128 v[180:183], v163 offset:1024
	ds_read_b128 v[184:187], v163 offset:2048
	ds_read_b128 v[188:191], v163 offset:3072
	ds_read_b128 v[192:195], v163 offset:4096
	ds_read_b128 v[196:199], v163 offset:5120
	ds_read_b128 v[200:203], v163 offset:6144
	ds_read_b128 v[204:207], v163 offset:7168
	global_load_lds_dwordx4 v152, s[18:19]
	s_add_i32 m0, s37, 0xe000
	s_nop 0
	global_load_lds_dwordx4 v154, s[18:19]
	s_waitcnt vmcnt(8) lgkmcnt(0)
	s_barrier
	v_mfma_f32_16x16x32_bf16 v[124:127], v[128:131], v[176:179], v[124:127]
	v_mfma_f32_16x16x32_bf16 v[120:123], v[136:139], v[176:179], v[120:123]
	v_mfma_f32_16x16x32_bf16 v[108:111], v[128:131], v[184:187], v[108:111]
	v_mfma_f32_16x16x32_bf16 v[104:107], v[136:139], v[184:187], v[104:107]
	v_mfma_f32_16x16x32_bf16 v[92:95], v[128:131], v[192:195], v[92:95]
	v_mfma_f32_16x16x32_bf16 v[88:91], v[136:139], v[192:195], v[88:91]
	v_mfma_f32_16x16x32_bf16 v[76:79], v[128:131], v[200:203], v[76:79]
	v_mfma_f32_16x16x32_bf16 v[72:75], v[136:139], v[200:203], v[72:75]
	v_mfma_f32_16x16x32_bf16 v[124:127], v[132:135], v[180:183], v[124:127]
	v_mfma_f32_16x16x32_bf16 v[120:123], v[140:143], v[180:183], v[120:123]
	v_mfma_f32_16x16x32_bf16 v[108:111], v[132:135], v[188:191], v[108:111]
	v_mfma_f32_16x16x32_bf16 v[104:107], v[140:143], v[188:191], v[104:107]
	v_mfma_f32_16x16x32_bf16 v[92:95], v[132:135], v[196:199], v[92:95]
	v_mfma_f32_16x16x32_bf16 v[88:91], v[140:143], v[196:199], v[88:91]
	v_mfma_f32_16x16x32_bf16 v[76:79], v[132:135], v[204:207], v[76:79]
	v_mfma_f32_16x16x32_bf16 v[72:75], v[140:143], v[204:207], v[72:75]
	v_mfma_f32_16x16x32_bf16 v[116:119], v[156:159], v[176:179], v[116:119]
	v_mfma_f32_16x16x32_bf16 v[112:115], v[168:171], v[176:179], v[112:115]
	v_mfma_f32_16x16x32_bf16 v[100:103], v[156:159], v[184:187], v[100:103]
	v_mfma_f32_16x16x32_bf16 v[96:99], v[168:171], v[184:187], v[96:99]
	v_mfma_f32_16x16x32_bf16 v[84:87], v[156:159], v[192:195], v[84:87]
	v_mfma_f32_16x16x32_bf16 v[80:83], v[168:171], v[192:195], v[80:83]
	v_mfma_f32_16x16x32_bf16 v[68:71], v[156:159], v[200:203], v[68:71]
	v_mfma_f32_16x16x32_bf16 v[64:67], v[168:171], v[200:203], v[64:67]
	v_mfma_f32_16x16x32_bf16 v[116:119], v[164:167], v[180:183], v[116:119]
	v_mfma_f32_16x16x32_bf16 v[112:115], v[172:175], v[180:183], v[112:115]
	v_mfma_f32_16x16x32_bf16 v[100:103], v[164:167], v[188:191], v[100:103]
	v_mfma_f32_16x16x32_bf16 v[96:99], v[172:175], v[188:191], v[96:99]
	v_mfma_f32_16x16x32_bf16 v[84:87], v[164:167], v[196:199], v[84:87]
	v_mfma_f32_16x16x32_bf16 v[80:83], v[172:175], v[196:199], v[80:83]
	v_mfma_f32_16x16x32_bf16 v[68:71], v[164:167], v[204:207], v[68:71]
	v_mfma_f32_16x16x32_bf16 v[64:67], v[172:175], v[204:207], v[64:67]
	s_add_i32 s69, s69, s30
	s_mov_b32 m0, s69
	ds_read_b128 v[176:179], v163 offset:16384
	ds_read_b128 v[180:183], v163 offset:17408
	ds_read_b128 v[184:187], v163 offset:18432
	ds_read_b128 v[188:191], v163 offset:19456
	ds_read_b128 v[192:195], v163 offset:20480
	ds_read_b128 v[196:199], v163 offset:21504
	ds_read_b128 v[200:203], v163 offset:22528
	ds_read_b128 v[204:207], v163 offset:23552
	global_load_lds_dwordx4 v148, s[62:63]
	s_add_i32 m0, s69, 0x2000
	s_add_u32 s70, s62, 0x4000
	s_addc_u32 s71, s63, 0
	s_add_i32 s69, s72, s30
	global_load_lds_dwordx4 v144, s[62:63]
	s_mov_b32 m0, s69
	s_nop 0
	global_load_lds_dwordx4 v148, s[70:71]
	s_add_i32 m0, s69, 0x2000
	s_nop 0
	global_load_lds_dwordx4 v144, s[70:71]
	s_mov_b32 m0, s37
	s_nop 0
	global_load_lds_dwordx4 v150, s[64:65]
	s_mov_b32 m0, s39
	s_nop 0
	global_load_lds_dwordx4 v146, s[64:65]
	s_waitcnt vmcnt(8) lgkmcnt(0)
	s_barrier
; #define PG8_STAGE(bufoff, gbase, voff) do { _Pragma("unroll") for (int _i = 0; _i < 2; ++_i) \
;         __builtin_amdgcn_global_load_lds((const unsigned*)((const char*)(gbase) + (voff)[_i]), (PG8_LAS unsigned*)(lds + (bufoff) + ldsw + _i * 8192), 16, 0, 0); } while (0)
; #define PG8_LDA(dst, b, h) do { _Pragma("unroll") for (int m = 0; m < 4; ++m) _Pragma("unroll") for (int k = 0; k < 2; ++k) dst[m][k] = *(const PG8_LAS bf16x8*)(lds + PG8_SA(b, h) + aoff + m * 2048 + k * 1024); } while (0)
; #define PG8_LDB(dst, b, h) do { _Pragma("unroll") for (int n = 0; n < 2; ++n) _Pragma("unroll") for (int k = 0; k < 2; ++k) dst[n][k] = *(const PG8_LAS bf16x8*)(lds + PG8_SB(b, h) + boff + n * 2048 + k * 1024); } while (0)
; #define PG8_MMA(ai, bj, At, Bt) do { __builtin_amdgcn_s_setprio(1); _Pragma("unroll") for (int m = 0; m < 4; ++m) _Pragma("unroll") for (int n = 0; n < 2; ++n) _Pragma("unroll") for (int k = 0; k < 2; ++k) \
;         acc[ai][bj][m][n] = __builtin_amdgcn_mfma_f32_16x16x32_bf16(Bt[n][k], At[m][k], acc[ai][bj][m][n], 0, 0, 0); __builtin_amdgcn_s_setprio(0); } while (0)
; #define PG8_WAIT_V(n) asm volatile("s_waitcnt vmcnt(" #n ")" ::: "memory")
; #define PG8_WAIT_L(n) asm volatile("s_waitcnt lgkmcnt(" #n ")" ::: "memory")
; #define PG8_BAR __builtin_amdgcn_s_barrier()
; #define PG8_SCHED __builtin_amdgcn_sched_barrier(0)
; template <class Epi, class Sched, bool ALIGN_EPI = false, bool SP2 = false>
; __device__ __forceinline__ void gemm_phase(PG8_LAS unsigned char* lds, const Gemm g, const Sched& S, const Epi& E) {
;     ...
;             PG8_WAIT_V(8); PG8_WAIT_L(0); PG8_BAR; PG8_MMA(1, 0, At, B0); PG8_MMA(1, 1, At, B1); PG8_BAR; PG8_SCHED;
;             PG8_LDB(B0, 1, 0); PG8_LDB(B1, 1, 1); PG8_SCHED; PG8_LDA(At, 1, 0); PG8_STAGE(PG8_SA(0, 1), a2 + hstep, voffA);
;             PG8_WAIT_V(8); PG8_WAIT_L(0); PG8_BAR; PG8_MMA(0, 0, At, B0); PG8_MMA(0, 1, At, B1); PG8_BAR; PG8_SCHED;
;             PG8_LDA(At, 1, 1); PG8_STAGE(PG8_SB(1, 0), b3, voffB); PG8_STAGE(PG8_SB(1, 1), b3 + hstep, voffB); PG8_STAGE(PG8_SA(1, 0), a3, voffA);
;             PG8_WAIT_V(8); PG8_WAIT_L(0); PG8_BAR; PG8_MMA(1, 0, At, B0); PG8_MMA(1, 1, At, B1); PG8_BAR; PG8_SCHED;
	v_mfma_f32_16x16x32_bf16 v[60:63], v[128:131], v[176:179], v[60:63]
	v_mfma_f32_16x16x32_bf16 v[56:59], v[136:139], v[176:179], v[56:59]
	v_mfma_f32_16x16x32_bf16 v[44:47], v[128:131], v[184:187], v[44:47]
	v_mfma_f32_16x16x32_bf16 v[40:43], v[136:139], v[184:187], v[40:43]
	v_mfma_f32_16x16x32_bf16 v[28:31], v[128:131], v[192:195], v[28:31]
	v_mfma_f32_16x16x32_bf16 v[24:27], v[136:139], v[192:195], v[24:27]
	v_mfma_f32_16x16x32_bf16 v[12:15], v[128:131], v[200:203], v[12:15]
	v_mfma_f32_16x16x32_bf16 v[8:11], v[136:139], v[200:203], v[8:11]
	v_mfma_f32_16x16x32_bf16 v[60:63], v[132:135], v[180:183], v[60:63]
	v_mfma_f32_16x16x32_bf16 v[56:59], v[140:143], v[180:183], v[56:59]
	v_mfma_f32_16x16x32_bf16 v[44:47], v[132:135], v[188:191], v[44:47]
	v_mfma_f32_16x16x32_bf16 v[40:43], v[140:143], v[188:191], v[40:43]
	v_mfma_f32_16x16x32_bf16 v[28:31], v[132:135], v[196:199], v[28:31]
	v_mfma_f32_16x16x32_bf16 v[24:27], v[140:143], v[196:199], v[24:27]
	v_mfma_f32_16x16x32_bf16 v[12:15], v[132:135], v[204:207], v[12:15]
	v_mfma_f32_16x16x32_bf16 v[8:11], v[140:143], v[204:207], v[8:11]
	v_mfma_f32_16x16x32_bf16 v[52:55], v[156:159], v[176:179], v[52:55]
	v_mfma_f32_16x16x32_bf16 v[48:51], v[168:171], v[176:179], v[48:51]
	v_mfma_f32_16x16x32_bf16 v[36:39], v[156:159], v[184:187], v[36:39]
	v_mfma_f32_16x16x32_bf16 v[32:35], v[168:171], v[184:187], v[32:35]
	v_mfma_f32_16x16x32_bf16 v[20:23], v[156:159], v[192:195], v[20:23]
	v_mfma_f32_16x16x32_bf16 v[16:19], v[168:171], v[192:195], v[16:19]
	v_mfma_f32_16x16x32_bf16 v[4:7], v[156:159], v[200:203], v[4:7]
	v_mfma_f32_16x16x32_bf16 v[0:3], v[168:171], v[200:203], v[0:3]
	v_mfma_f32_16x16x32_bf16 v[52:55], v[164:167], v[180:183], v[52:55]
	v_mfma_f32_16x16x32_bf16 v[48:51], v[172:175], v[180:183], v[48:51]
	v_mfma_f32_16x16x32_bf16 v[36:39], v[164:167], v[188:191], v[36:39]
	v_mfma_f32_16x16x32_bf16 v[32:35], v[172:175], v[188:191], v[32:35]
	v_mfma_f32_16x16x32_bf16 v[20:23], v[164:167], v[196:199], v[20:23]
	v_mfma_f32_16x16x32_bf16 v[16:19], v[172:175], v[196:199], v[16:19]
	v_mfma_f32_16x16x32_bf16 v[4:7], v[164:167], v[204:207], v[4:7]
	v_mfma_f32_16x16x32_bf16 v[0:3], v[172:175], v[204:207], v[0:3]
	s_add_i32 s69, 0, 0x18000
	s_add_i32 s70, 0, 0x1c000
	v_add_u32_e32 v140, s69, v162
	v_add_u32_e32 v160, s70, v162
	ds_read_b128 v[128:131], v140
	ds_read_b128 v[132:135], v140 offset:1024
	ds_read_b128 v[136:139], v140 offset:2048
	ds_read_b128 v[140:143], v140 offset:3072
	ds_read_b128 v[156:159], v160
	ds_read_b128 v[164:167], v160 offset:1024
	ds_read_b128 v[168:171], v160 offset:2048
	ds_read_b128 v[172:175], v160 offset:3072
	s_add_u32 s64, s64, 0x4000
	s_addc_u32 s65, s65, 0
	s_mov_b32 m0, s41
	ds_read_b128 v[176:179], v163 offset:32768
	ds_read_b128 v[180:183], v163 offset:33792
	ds_read_b128 v[184:187], v163 offset:34816
	ds_read_b128 v[188:191], v163 offset:35840
	ds_read_b128 v[192:195], v163 offset:36864
	ds_read_b128 v[196:199], v163 offset:37888
	ds_read_b128 v[200:203], v163 offset:38912
	ds_read_b128 v[204:207], v163 offset:39936
	global_load_lds_dwordx4 v150, s[64:65]
	s_mov_b32 m0, s42
	s_nop 0
	global_load_lds_dwordx4 v146, s[64:65]
	s_waitcnt vmcnt(8) lgkmcnt(0)
	s_barrier
	v_mfma_f32_16x16x32_bf16 v[124:127], v[128:131], v[176:179], v[124:127]
	v_mfma_f32_16x16x32_bf16 v[120:123], v[136:139], v[176:179], v[120:123]
	v_mfma_f32_16x16x32_bf16 v[108:111], v[128:131], v[184:187], v[108:111]
	v_mfma_f32_16x16x32_bf16 v[104:107], v[136:139], v[184:187], v[104:107]
	v_mfma_f32_16x16x32_bf16 v[92:95], v[128:131], v[192:195], v[92:95]
	v_mfma_f32_16x16x32_bf16 v[88:91], v[136:139], v[192:195], v[88:91]
	v_mfma_f32_16x16x32_bf16 v[76:79], v[128:131], v[200:203], v[76:79]
	v_mfma_f32_16x16x32_bf16 v[72:75], v[136:139], v[200:203], v[72:75]
	v_mfma_f32_16x16x32_bf16 v[124:127], v[132:135], v[180:183], v[124:127]
	v_mfma_f32_16x16x32_bf16 v[120:123], v[140:143], v[180:183], v[120:123]
	v_mfma_f32_16x16x32_bf16 v[108:111], v[132:135], v[188:191], v[108:111]
	v_mfma_f32_16x16x32_bf16 v[104:107], v[140:143], v[188:191], v[104:107]
	v_mfma_f32_16x16x32_bf16 v[92:95], v[132:135], v[196:199], v[92:95]
	v_mfma_f32_16x16x32_bf16 v[88:91], v[140:143], v[196:199], v[88:91]
	v_mfma_f32_16x16x32_bf16 v[76:79], v[132:135], v[204:207], v[76:79]
	v_mfma_f32_16x16x32_bf16 v[72:75], v[140:143], v[204:207], v[72:75]
	v_mfma_f32_16x16x32_bf16 v[116:119], v[156:159], v[176:179], v[116:119]
	v_mfma_f32_16x16x32_bf16 v[112:115], v[168:171], v[176:179], v[112:115]
	v_mfma_f32_16x16x32_bf16 v[100:103], v[156:159], v[184:187], v[100:103]
	v_mfma_f32_16x16x32_bf16 v[96:99], v[168:171], v[184:187], v[96:99]
	v_mfma_f32_16x16x32_bf16 v[84:87], v[156:159], v[192:195], v[84:87]
	v_mfma_f32_16x16x32_bf16 v[80:83], v[168:171], v[192:195], v[80:83]
	v_mfma_f32_16x16x32_bf16 v[68:71], v[156:159], v[200:203], v[68:71]
	v_mfma_f32_16x16x32_bf16 v[64:67], v[168:171], v[200:203], v[64:67]
	v_mfma_f32_16x16x32_bf16 v[116:119], v[164:167], v[180:183], v[116:119]
	v_mfma_f32_16x16x32_bf16 v[112:115], v[172:175], v[180:183], v[112:115]
	v_mfma_f32_16x16x32_bf16 v[100:103], v[164:167], v[188:191], v[100:103]
	v_mfma_f32_16x16x32_bf16 v[96:99], v[172:175], v[188:191], v[96:99]
	v_mfma_f32_16x16x32_bf16 v[84:87], v[164:167], v[196:199], v[84:87]
	v_mfma_f32_16x16x32_bf16 v[80:83], v[172:175], v[196:199], v[80:83]
	v_mfma_f32_16x16x32_bf16 v[68:71], v[164:167], v[204:207], v[68:71]
	v_mfma_f32_16x16x32_bf16 v[64:67], v[172:175], v[204:207], v[64:67]
	s_add_u32 s64, s62, 0x8000
	s_addc_u32 s65, s63, 0
	s_add_i32 s69, s69, s30
	s_mov_b32 m0, s69
	ds_read_b128 v[176:179], v163 offset:49152
	ds_read_b128 v[180:183], v163 offset:50176
	ds_read_b128 v[184:187], v163 offset:51200
	ds_read_b128 v[188:191], v163 offset:52224
	ds_read_b128 v[192:195], v163 offset:53248
	ds_read_b128 v[196:199], v163 offset:54272
	ds_read_b128 v[200:203], v163 offset:55296
	ds_read_b128 v[204:207], v163 offset:56320
	global_load_lds_dwordx4 v148, s[64:65]
	s_add_i32 m0, s69, 0x2000
	s_add_u32 s62, s62, 0xc000
	v_lshl_add_u64 v[160:161], s[64:65], 0, v[144:145]
	s_addc_u32 s63, s63, 0
	s_add_i32 s64, s70, s30
	global_load_lds_dwordx4 v[160:161], off
	s_mov_b32 m0, s64
	s_nop 0
	global_load_lds_dwordx4 v148, s[62:63]
	s_add_i32 m0, s64, 0x2000
	s_nop 0
	global_load_lds_dwordx4 v144, s[62:63]
	s_mov_b32 m0, s54
	s_nop 0
	global_load_lds_dwordx4 v150, s[20:21]
	s_mov_b32 m0, s55
	s_nop 0
	global_load_lds_dwordx4 v146, s[20:21]
	s_waitcnt vmcnt(8) lgkmcnt(0)
	s_barrier
; #define PG8_STAGE(bufoff, gbase, voff) do { _Pragma("unroll") for (int _i = 0; _i < 2; ++_i) \
;         __builtin_amdgcn_global_load_lds((const unsigned*)((const char*)(gbase) + (voff)[_i]), (PG8_LAS unsigned*)(lds + (bufoff) + ldsw + _i * 8192), 16, 0, 0); } while (0)
; #define PG8_LDA(dst, b, h) do { _Pragma("unroll") for (int m = 0; m < 4; ++m) _Pragma("unroll") for (int k = 0; k < 2; ++k) dst[m][k] = *(const PG8_LAS bf16x8*)(lds + PG8_SA(b, h) + aoff + m * 2048 + k * 1024); } while (0)
; #define PG8_LDB(dst, b, h) do { _Pragma("unroll") for (int n = 0; n < 2; ++n) _Pragma("unroll") for (int k = 0; k < 2; ++k) dst[n][k] = *(const PG8_LAS bf16x8*)(lds + PG8_SB(b, h) + boff + n * 2048 + k * 1024); } while (0)
; #define PG8_MMA(ai, bj, At, Bt) do { __builtin_amdgcn_s_setprio(1); _Pragma("unroll") for (int m = 0; m < 4; ++m) _Pragma("unroll") for (int n = 0; n < 2; ++n) _Pragma("unroll") for (int k = 0; k < 2; ++k) \
;         acc[ai][bj][m][n] = __builtin_amdgcn_mfma_f32_16x16x32_bf16(Bt[n][k], At[m][k], acc[ai][bj][m][n], 0, 0, 0); __builtin_amdgcn_s_setprio(0); } while (0)
; #define PG8_WAIT_V(n) asm volatile("s_waitcnt vmcnt(" #n ")" ::: "memory")
; #define PG8_WAIT_L(n) asm volatile("s_waitcnt lgkmcnt(" #n ")" ::: "memory")
; #define PG8_BAR __builtin_amdgcn_s_barrier()
; #define PG8_SCHED __builtin_amdgcn_sched_barrier(0)
; template <class Epi, class Sched, bool ALIGN_EPI = false, bool SP2 = false>
; __device__ __forceinline__ void gemm_phase(PG8_LAS unsigned char* lds, const Gemm g, const Sched& S, const Epi& E) {
;     ...
;         for (int t = 0; t < nt; t += 2) {
;             const bool last = (t == nt - 2);
;             const char* a1 = cA + (size_t)(t + 1) * kstep;
;             const char* a2 = last ? nA : cA + (size_t)(t + 2) * kstep; const char* b2 = last ? nB : cB + (size_t)(t + 2) * kstep;
;             const char* a3 = a2 + kstep; const char* b3 = b2 + kstep;
;             if (last && has_next) S.a_ready(nxt);
;             if constexpr (SP2) {
;             PG8_LDB(B0, 0, 0); PG8_LDB(B1, 0, 1); PG8_SCHED; PG8_LDA(At, 0, 0); PG8_STAGE(PG8_SA(1, 1), a1 + hstep, voffA);
;             PG8_WAIT_V(8); PG8_WAIT_L(0); PG8_BAR; PG8_MMA(0, 0, At, B0); PG8_MMA(0, 1, At, B1); PG8_BAR; PG8_SCHED;
;     ...
;             PG8_WAIT_V(8); PG8_WAIT_L(0); PG8_BAR; PG8_MMA(1, 0, At, B0); PG8_MMA(1, 1, At, B1); PG8_BAR; PG8_SCHED;
	v_mfma_f32_16x16x32_bf16 v[60:63], v[128:131], v[176:179], v[60:63]
	v_mfma_f32_16x16x32_bf16 v[56:59], v[136:139], v[176:179], v[56:59]
	v_mfma_f32_16x16x32_bf16 v[44:47], v[128:131], v[184:187], v[44:47]
	v_mfma_f32_16x16x32_bf16 v[40:43], v[136:139], v[184:187], v[40:43]
	v_mfma_f32_16x16x32_bf16 v[28:31], v[128:131], v[192:195], v[28:31]
	v_mfma_f32_16x16x32_bf16 v[24:27], v[136:139], v[192:195], v[24:27]
	v_mfma_f32_16x16x32_bf16 v[12:15], v[128:131], v[200:203], v[12:15]
	v_mfma_f32_16x16x32_bf16 v[8:11], v[136:139], v[200:203], v[8:11]
	v_mfma_f32_16x16x32_bf16 v[60:63], v[132:135], v[180:183], v[60:63]
	v_mfma_f32_16x16x32_bf16 v[56:59], v[140:143], v[180:183], v[56:59]
	v_mfma_f32_16x16x32_bf16 v[44:47], v[132:135], v[188:191], v[44:47]
	v_mfma_f32_16x16x32_bf16 v[40:43], v[140:143], v[188:191], v[40:43]
	v_mfma_f32_16x16x32_bf16 v[28:31], v[132:135], v[196:199], v[28:31]
	v_mfma_f32_16x16x32_bf16 v[24:27], v[140:143], v[196:199], v[24:27]
	v_mfma_f32_16x16x32_bf16 v[12:15], v[132:135], v[204:207], v[12:15]
	v_mfma_f32_16x16x32_bf16 v[8:11], v[140:143], v[204:207], v[8:11]
	v_mfma_f32_16x16x32_bf16 v[52:55], v[156:159], v[176:179], v[52:55]
	v_mfma_f32_16x16x32_bf16 v[48:51], v[168:171], v[176:179], v[48:51]
	v_mfma_f32_16x16x32_bf16 v[36:39], v[156:159], v[184:187], v[36:39]
	v_mfma_f32_16x16x32_bf16 v[32:35], v[168:171], v[184:187], v[32:35]
	v_mfma_f32_16x16x32_bf16 v[20:23], v[156:159], v[192:195], v[20:23]
	v_mfma_f32_16x16x32_bf16 v[16:19], v[168:171], v[192:195], v[16:19]
	v_mfma_f32_16x16x32_bf16 v[4:7], v[156:159], v[200:203], v[4:7]
	v_mfma_f32_16x16x32_bf16 v[0:3], v[168:171], v[200:203], v[0:3]
	v_mfma_f32_16x16x32_bf16 v[52:55], v[164:167], v[180:183], v[52:55]
	v_mfma_f32_16x16x32_bf16 v[48:51], v[172:175], v[180:183], v[48:51]
	v_mfma_f32_16x16x32_bf16 v[36:39], v[164:167], v[188:191], v[36:39]
	v_mfma_f32_16x16x32_bf16 v[32:35], v[172:175], v[188:191], v[32:35]
	v_mfma_f32_16x16x32_bf16 v[20:23], v[164:167], v[196:199], v[20:23]
	v_mfma_f32_16x16x32_bf16 v[16:19], v[172:175], v[196:199], v[16:19]
	v_mfma_f32_16x16x32_bf16 v[4:7], v[164:167], v[204:207], v[4:7]
	v_mfma_f32_16x16x32_bf16 v[0:3], v[172:175], v[204:207], v[0:3]
	s_add_i32 s68, s68, 2
	s_add_u32 s18, s18, 0x10000
	s_addc_u32 s19, s19, 0
	s_add_u32 s66, s66, 0x10000
	s_addc_u32 s67, s67, 0
	s_cmp_gt_u32 s68, 13
	s_cbranch_scc0 .Lk0_lead
	s_branch .Lk0_done
.Lk0_trail:
	s_add_u32 s20, s18, 0x4000
	s_addc_u32 s21, s19, 0
	s_cmp_eq_u32 s68, 12
	s_cselect_b32 s64, s40, s20
	s_cselect_b32 s65, s11, s21
	s_cselect_b32 s62, s61, s66
	s_cselect_b32 s63, s9, s67
	s_add_u32 s20, s64, 0x8000
	s_addc_u32 s21, s65, 0
	s_add_i32 s69, 0, 0x10000
	s_add_i32 s72, 0, 0x14000
	v_add_u32_e32 v140, s69, v162
	v_add_u32_e32 v160, s72, v162
	ds_read_b128 v[128:131], v140
	ds_read_b128 v[132:135], v140 offset:1024
	ds_read_b128 v[136:139], v140 offset:2048
	ds_read_b128 v[140:143], v140 offset:3072
	ds_read_b128 v[156:159], v160
	ds_read_b128 v[164:167], v160 offset:1024
	ds_read_b128 v[168:171], v160 offset:2048
	ds_read_b128 v[172:175], v160 offset:3072
	s_add_i32 m0, s37, 0xc000
	ds_read_b128 v[176:179], v163
	ds_read_b128 v[180:183], v163 offset:1024
	ds_read_b128 v[184:187], v163 offset:2048
	ds_read_b128 v[188:191], v163 offset:3072
	ds_read_b128 v[192:195], v163 offset:4096
	ds_read_b128 v[196:199], v163 offset:5120
	ds_read_b128 v[200:203], v163 offset:6144
	ds_read_b128 v[204:207], v163 offset:7168
	global_load_lds_dwordx4 v152, s[18:19]
	s_add_i32 m0, s37, 0xe000
	s_nop 0
	global_load_lds_dwordx4 v154, s[18:19]
	s_waitcnt vmcnt(8) lgkmcnt(0)
	v_mfma_f32_16x16x32_bf16 v[124:127], v[128:131], v[176:179], v[124:127]
	v_mfma_f32_16x16x32_bf16 v[120:123], v[136:139], v[176:179], v[120:123]
	v_mfma_f32_16x16x32_bf16 v[108:111], v[128:131], v[184:187], v[108:111]
	v_mfma_f32_16x16x32_bf16 v[104:107], v[136:139], v[184:187], v[104:107]
	v_mfma_f32_16x16x32_bf16 v[92:95], v[128:131], v[192:195], v[92:95]
	v_mfma_f32_16x16x32_bf16 v[88:91], v[136:139], v[192:195], v[88:91]
	v_mfma_f32_16x16x32_bf16 v[76:79], v[128:131], v[200:203], v[76:79]
	v_mfma_f32_16x16x32_bf16 v[72:75], v[136:139], v[200:203], v[72:75]
	v_mfma_f32_16x16x32_bf16 v[124:127], v[132:135], v[180:183], v[124:127]
	v_mfma_f32_16x16x32_bf16 v[120:123], v[140:143], v[180:183], v[120:123]
	v_mfma_f32_16x16x32_bf16 v[108:111], v[132:135], v[188:191], v[108:111]
	v_mfma_f32_16x16x32_bf16 v[104:107], v[140:143], v[188:191], v[104:107]
	v_mfma_f32_16x16x32_bf16 v[92:95], v[132:135], v[196:199], v[92:95]
	v_mfma_f32_16x16x32_bf16 v[88:91], v[140:143], v[196:199], v[88:91]
	v_mfma_f32_16x16x32_bf16 v[76:79], v[132:135], v[204:207], v[76:79]
	v_mfma_f32_16x16x32_bf16 v[72:75], v[140:143], v[204:207], v[72:75]
	v_mfma_f32_16x16x32_bf16 v[116:119], v[156:159], v[176:179], v[116:119]
	v_mfma_f32_16x16x32_bf16 v[112:115], v[168:171], v[176:179], v[112:115]
	v_mfma_f32_16x16x32_bf16 v[100:103], v[156:159], v[184:187], v[100:103]
	v_mfma_f32_16x16x32_bf16 v[96:99], v[168:171], v[184:187], v[96:99]
	v_mfma_f32_16x16x32_bf16 v[84:87], v[156:159], v[192:195], v[84:87]
	v_mfma_f32_16x16x32_bf16 v[80:83], v[168:171], v[192:195], v[80:83]
	v_mfma_f32_16x16x32_bf16 v[68:71], v[156:159], v[200:203], v[68:71]
	v_mfma_f32_16x16x32_bf16 v[64:67], v[168:171], v[200:203], v[64:67]
	v_mfma_f32_16x16x32_bf16 v[116:119], v[164:167], v[180:183], v[116:119]
	v_mfma_f32_16x16x32_bf16 v[112:115], v[172:175], v[180:183], v[112:115]
	v_mfma_f32_16x16x32_bf16 v[100:103], v[164:167], v[188:191], v[100:103]
	v_mfma_f32_16x16x32_bf16 v[96:99], v[172:175], v[188:191], v[96:99]
	v_mfma_f32_16x16x32_bf16 v[84:87], v[164:167], v[196:199], v[84:87]
	v_mfma_f32_16x16x32_bf16 v[80:83], v[172:175], v[196:199], v[80:83]
	v_mfma_f32_16x16x32_bf16 v[68:71], v[164:167], v[204:207], v[68:71]
	v_mfma_f32_16x16x32_bf16 v[64:67], v[172:175], v[204:207], v[64:67]
	s_barrier
; #define PG8_STAGE(bufoff, gbase, voff) do { _Pragma("unroll") for (int _i = 0; _i < 2; ++_i) \
;         __builtin_amdgcn_global_load_lds((const unsigned*)((const char*)(gbase) + (voff)[_i]), (PG8_LAS unsigned*)(lds + (bufoff) + ldsw + _i * 8192), 16, 0, 0); } while (0)
; #define PG8_LDA(dst, b, h) do { _Pragma("unroll") for (int m = 0; m < 4; ++m) _Pragma("unroll") for (int k = 0; k < 2; ++k) dst[m][k] = *(const PG8_LAS bf16x8*)(lds + PG8_SA(b, h) + aoff + m * 2048 + k * 1024); } while (0)
; #define PG8_LDB(dst, b, h) do { _Pragma("unroll") for (int n = 0; n < 2; ++n) _Pragma("unroll") for (int k = 0; k < 2; ++k) dst[n][k] = *(const PG8_LAS bf16x8*)(lds + PG8_SB(b, h) + boff + n * 2048 + k * 1024); } while (0)
; #define PG8_MMA(ai, bj, At, Bt) do { __builtin_amdgcn_s_setprio(1); _Pragma("unroll") for (int m = 0; m < 4; ++m) _Pragma("unroll") for (int n = 0; n < 2; ++n) _Pragma("unroll") for (int k = 0; k < 2; ++k) \
;         acc[ai][bj][m][n] = __builtin_amdgcn_mfma_f32_16x16x32_bf16(Bt[n][k], At[m][k], acc[ai][bj][m][n], 0, 0, 0); __builtin_amdgcn_s_setprio(0); } while (0)
; #define PG8_WAIT_V(n) asm volatile("s_waitcnt vmcnt(" #n ")" ::: "memory")
; #define PG8_WAIT_L(n) asm volatile("s_waitcnt lgkmcnt(" #n ")" ::: "memory")
; #define PG8_BAR __builtin_amdgcn_s_barrier()
; #define PG8_SCHED __builtin_amdgcn_sched_barrier(0)
; template <class Epi, class Sched, bool ALIGN_EPI = false, bool SP2 = false>
; __device__ __forceinline__ void gemm_phase(PG8_LAS unsigned char* lds, const Gemm g, const Sched& S, const Epi& E) {
;     ...
;             PG8_LDA(At, 0, 1); PG8_STAGE(PG8_SB(0, 0), b2, voffB); PG8_STAGE(PG8_SB(0, 1), b2 + hstep, voffB); PG8_STAGE(PG8_SA(0, 0), a2, voffA);
;             PG8_WAIT_V(8); PG8_WAIT_L(0); PG8_BAR; PG8_MMA(1, 0, At, B0); PG8_MMA(1, 1, At, B1); PG8_BAR; PG8_SCHED;
;             PG8_LDB(B0, 1, 0); PG8_LDB(B1, 1, 1); PG8_SCHED; PG8_LDA(At, 1, 0); PG8_STAGE(PG8_SA(0, 1), a2 + hstep, voffA);
;             PG8_WAIT_V(8); PG8_WAIT_L(0); PG8_BAR; PG8_MMA(0, 0, At, B0); PG8_MMA(0, 1, At, B1); PG8_BAR; PG8_SCHED;
;             PG8_LDA(At, 1, 1); PG8_STAGE(PG8_SB(1, 0), b3, voffB); PG8_STAGE(PG8_SB(1, 1), b3 + hstep, voffB); PG8_STAGE(PG8_SA(1, 0), a3, voffA);
	s_add_i32 s69, s69, s30
	s_mov_b32 m0, s69
	ds_read_b128 v[176:179], v163 offset:16384
	ds_read_b128 v[180:183], v163 offset:17408
	ds_read_b128 v[184:187], v163 offset:18432
	ds_read_b128 v[188:191], v163 offset:19456
	ds_read_b128 v[192:195], v163 offset:20480
	ds_read_b128 v[196:199], v163 offset:21504
	ds_read_b128 v[200:203], v163 offset:22528
	ds_read_b128 v[204:207], v163 offset:23552
	global_load_lds_dwordx4 v148, s[62:63]
	s_add_i32 m0, s69, 0x2000
	s_add_u32 s70, s62, 0x4000
	s_addc_u32 s71, s63, 0
	s_add_i32 s69, s72, s30
	global_load_lds_dwordx4 v144, s[62:63]
	s_mov_b32 m0, s69
	s_nop 0
	global_load_lds_dwordx4 v148, s[70:71]
	s_add_i32 m0, s69, 0x2000
	s_nop 0
	global_load_lds_dwordx4 v144, s[70:71]
	s_mov_b32 m0, s37
	s_nop 0
	global_load_lds_dwordx4 v150, s[64:65]
	s_mov_b32 m0, s39
	s_nop 0
	global_load_lds_dwordx4 v146, s[64:65]
	s_waitcnt vmcnt(8) lgkmcnt(0)
	v_mfma_f32_16x16x32_bf16 v[60:63], v[128:131], v[176:179], v[60:63]
	v_mfma_f32_16x16x32_bf16 v[56:59], v[136:139], v[176:179], v[56:59]
	v_mfma_f32_16x16x32_bf16 v[44:47], v[128:131], v[184:187], v[44:47]
	v_mfma_f32_16x16x32_bf16 v[40:43], v[136:139], v[184:187], v[40:43]
	v_mfma_f32_16x16x32_bf16 v[28:31], v[128:131], v[192:195], v[28:31]
	v_mfma_f32_16x16x32_bf16 v[24:27], v[136:139], v[192:195], v[24:27]
	v_mfma_f32_16x16x32_bf16 v[12:15], v[128:131], v[200:203], v[12:15]
	v_mfma_f32_16x16x32_bf16 v[8:11], v[136:139], v[200:203], v[8:11]
	v_mfma_f32_16x16x32_bf16 v[60:63], v[132:135], v[180:183], v[60:63]
	v_mfma_f32_16x16x32_bf16 v[56:59], v[140:143], v[180:183], v[56:59]
	v_mfma_f32_16x16x32_bf16 v[44:47], v[132:135], v[188:191], v[44:47]
	v_mfma_f32_16x16x32_bf16 v[40:43], v[140:143], v[188:191], v[40:43]
	v_mfma_f32_16x16x32_bf16 v[28:31], v[132:135], v[196:199], v[28:31]
	v_mfma_f32_16x16x32_bf16 v[24:27], v[140:143], v[196:199], v[24:27]
	v_mfma_f32_16x16x32_bf16 v[12:15], v[132:135], v[204:207], v[12:15]
	v_mfma_f32_16x16x32_bf16 v[8:11], v[140:143], v[204:207], v[8:11]
	v_mfma_f32_16x16x32_bf16 v[52:55], v[156:159], v[176:179], v[52:55]
	v_mfma_f32_16x16x32_bf16 v[48:51], v[168:171], v[176:179], v[48:51]
	v_mfma_f32_16x16x32_bf16 v[36:39], v[156:159], v[184:187], v[36:39]
	v_mfma_f32_16x16x32_bf16 v[32:35], v[168:171], v[184:187], v[32:35]
	v_mfma_f32_16x16x32_bf16 v[20:23], v[156:159], v[192:195], v[20:23]
	v_mfma_f32_16x16x32_bf16 v[16:19], v[168:171], v[192:195], v[16:19]
	v_mfma_f32_16x16x32_bf16 v[4:7], v[156:159], v[200:203], v[4:7]
	v_mfma_f32_16x16x32_bf16 v[0:3], v[168:171], v[200:203], v[0:3]
	v_mfma_f32_16x16x32_bf16 v[52:55], v[164:167], v[180:183], v[52:55]
	v_mfma_f32_16x16x32_bf16 v[48:51], v[172:175], v[180:183], v[48:51]
	v_mfma_f32_16x16x32_bf16 v[36:39], v[164:167], v[188:191], v[36:39]
	v_mfma_f32_16x16x32_bf16 v[32:35], v[172:175], v[188:191], v[32:35]
	v_mfma_f32_16x16x32_bf16 v[20:23], v[164:167], v[196:199], v[20:23]
	v_mfma_f32_16x16x32_bf16 v[16:19], v[172:175], v[196:199], v[16:19]
	v_mfma_f32_16x16x32_bf16 v[4:7], v[164:167], v[204:207], v[4:7]
	v_mfma_f32_16x16x32_bf16 v[0:3], v[172:175], v[204:207], v[0:3]
	s_barrier
	s_add_i32 s69, 0, 0x18000
	s_add_i32 s70, 0, 0x1c000
	v_add_u32_e32 v140, s69, v162
	v_add_u32_e32 v160, s70, v162
	ds_read_b128 v[128:131], v140
	ds_read_b128 v[132:135], v140 offset:1024
	ds_read_b128 v[136:139], v140 offset:2048
	ds_read_b128 v[140:143], v140 offset:3072
	ds_read_b128 v[156:159], v160
	ds_read_b128 v[164:167], v160 offset:1024
	ds_read_b128 v[168:171], v160 offset:2048
	ds_read_b128 v[172:175], v160 offset:3072
	s_add_u32 s64, s64, 0x4000
	s_addc_u32 s65, s65, 0
	s_mov_b32 m0, s41
	ds_read_b128 v[176:179], v163 offset:32768
	ds_read_b128 v[180:183], v163 offset:33792
	ds_read_b128 v[184:187], v163 offset:34816
	ds_read_b128 v[188:191], v163 offset:35840
	ds_read_b128 v[192:195], v163 offset:36864
	ds_read_b128 v[196:199], v163 offset:37888
	ds_read_b128 v[200:203], v163 offset:38912
	ds_read_b128 v[204:207], v163 offset:39936
	global_load_lds_dwordx4 v150, s[64:65]
	s_mov_b32 m0, s42
	s_nop 0
	global_load_lds_dwordx4 v146, s[64:65]
	s_waitcnt vmcnt(8) lgkmcnt(0)
	v_mfma_f32_16x16x32_bf16 v[124:127], v[128:131], v[176:179], v[124:127]
	v_mfma_f32_16x16x32_bf16 v[120:123], v[136:139], v[176:179], v[120:123]
	v_mfma_f32_16x16x32_bf16 v[108:111], v[128:131], v[184:187], v[108:111]
	v_mfma_f32_16x16x32_bf16 v[104:107], v[136:139], v[184:187], v[104:107]
	v_mfma_f32_16x16x32_bf16 v[92:95], v[128:131], v[192:195], v[92:95]
	v_mfma_f32_16x16x32_bf16 v[88:91], v[136:139], v[192:195], v[88:91]
	v_mfma_f32_16x16x32_bf16 v[76:79], v[128:131], v[200:203], v[76:79]
	v_mfma_f32_16x16x32_bf16 v[72:75], v[136:139], v[200:203], v[72:75]
	v_mfma_f32_16x16x32_bf16 v[124:127], v[132:135], v[180:183], v[124:127]
	v_mfma_f32_16x16x32_bf16 v[120:123], v[140:143], v[180:183], v[120:123]
	v_mfma_f32_16x16x32_bf16 v[108:111], v[132:135], v[188:191], v[108:111]
	v_mfma_f32_16x16x32_bf16 v[104:107], v[140:143], v[188:191], v[104:107]
	v_mfma_f32_16x16x32_bf16 v[92:95], v[132:135], v[196:199], v[92:95]
	v_mfma_f32_16x16x32_bf16 v[88:91], v[140:143], v[196:199], v[88:91]
	v_mfma_f32_16x16x32_bf16 v[76:79], v[132:135], v[204:207], v[76:79]
	v_mfma_f32_16x16x32_bf16 v[72:75], v[140:143], v[204:207], v[72:75]
	v_mfma_f32_16x16x32_bf16 v[116:119], v[156:159], v[176:179], v[116:119]
	v_mfma_f32_16x16x32_bf16 v[112:115], v[168:171], v[176:179], v[112:115]
	v_mfma_f32_16x16x32_bf16 v[100:103], v[156:159], v[184:187], v[100:103]
	v_mfma_f32_16x16x32_bf16 v[96:99], v[168:171], v[184:187], v[96:99]
	v_mfma_f32_16x16x32_bf16 v[84:87], v[156:159], v[192:195], v[84:87]
	v_mfma_f32_16x16x32_bf16 v[80:83], v[168:171], v[192:195], v[80:83]
	v_mfma_f32_16x16x32_bf16 v[68:71], v[156:159], v[200:203], v[68:71]
	v_mfma_f32_16x16x32_bf16 v[64:67], v[168:171], v[200:203], v[64:67]
	v_mfma_f32_16x16x32_bf16 v[116:119], v[164:167], v[180:183], v[116:119]
	v_mfma_f32_16x16x32_bf16 v[112:115], v[172:175], v[180:183], v[112:115]
	v_mfma_f32_16x16x32_bf16 v[100:103], v[164:167], v[188:191], v[100:103]
	v_mfma_f32_16x16x32_bf16 v[96:99], v[172:175], v[188:191], v[96:99]
	v_mfma_f32_16x16x32_bf16 v[84:87], v[164:167], v[196:199], v[84:87]
	v_mfma_f32_16x16x32_bf16 v[80:83], v[172:175], v[196:199], v[80:83]
	v_mfma_f32_16x16x32_bf16 v[68:71], v[164:167], v[204:207], v[68:71]
	v_mfma_f32_16x16x32_bf16 v[64:67], v[172:175], v[204:207], v[64:67]
	s_barrier
; #define PG8_STAGE(bufoff, gbase, voff) do { _Pragma("unroll") for (int _i = 0; _i < 2; ++_i) \
;         __builtin_amdgcn_global_load_lds((const unsigned*)((const char*)(gbase) + (voff)[_i]), (PG8_LAS unsigned*)(lds + (bufoff) + ldsw + _i * 8192), 16, 0, 0); } while (0)
; #define PG8_LDA(dst, b, h) do { _Pragma("unroll") for (int m = 0; m < 4; ++m) _Pragma("unroll") for (int k = 0; k < 2; ++k) dst[m][k] = *(const PG8_LAS bf16x8*)(lds + PG8_SA(b, h) + aoff + m * 2048 + k * 1024); } while (0)
; #define PG8_MMA(ai, bj, At, Bt) do { __builtin_amdgcn_s_setprio(1); _Pragma("unroll") for (int m = 0; m < 4; ++m) _Pragma("unroll") for (int n = 0; n < 2; ++n) _Pragma("unroll") for (int k = 0; k < 2; ++k) \
;         acc[ai][bj][m][n] = __builtin_amdgcn_mfma_f32_16x16x32_bf16(Bt[n][k], At[m][k], acc[ai][bj][m][n], 0, 0, 0); __builtin_amdgcn_s_setprio(0); } while (0)
; #define PG8_WAIT_V(n) asm volatile("s_waitcnt vmcnt(" #n ")" ::: "memory")
; #define PG8_WAIT_L(n) asm volatile("s_waitcnt lgkmcnt(" #n ")" ::: "memory")
; #define PG8_BAR __builtin_amdgcn_s_barrier()
; #define PG8_SCHED __builtin_amdgcn_sched_barrier(0)
; template <class Epi, class Sched, bool ALIGN_EPI = false, bool SP2 = false>
; __device__ __forceinline__ void gemm_phase(PG8_LAS unsigned char* lds, const Gemm g, const Sched& S, const Epi& E) {
;     ...
;         for (int t = 0; t < nt; t += 2) {
;             const bool last = (t == nt - 2);
;     ...
;             PG8_LDA(At, 1, 1); PG8_STAGE(PG8_SB(1, 0), b3, voffB); PG8_STAGE(PG8_SB(1, 1), b3 + hstep, voffB); PG8_STAGE(PG8_SA(1, 0), a3, voffA);
;             PG8_WAIT_V(8); PG8_WAIT_L(0); PG8_BAR; PG8_MMA(1, 0, At, B0); PG8_MMA(1, 1, At, B1); PG8_BAR; PG8_SCHED;
	s_add_u32 s64, s62, 0x8000
	s_addc_u32 s65, s63, 0
	s_add_i32 s69, s69, s30
	s_mov_b32 m0, s69
	ds_read_b128 v[176:179], v163 offset:49152
	ds_read_b128 v[180:183], v163 offset:50176
	ds_read_b128 v[184:187], v163 offset:51200
	ds_read_b128 v[188:191], v163 offset:52224
	ds_read_b128 v[192:195], v163 offset:53248
	ds_read_b128 v[196:199], v163 offset:54272
	ds_read_b128 v[200:203], v163 offset:55296
	ds_read_b128 v[204:207], v163 offset:56320
	global_load_lds_dwordx4 v148, s[64:65]
	s_add_i32 m0, s69, 0x2000
	s_add_u32 s62, s62, 0xc000
	v_lshl_add_u64 v[160:161], s[64:65], 0, v[144:145]
	s_addc_u32 s63, s63, 0
	s_add_i32 s64, s70, s30
	global_load_lds_dwordx4 v[160:161], off
	s_mov_b32 m0, s64
	s_nop 0
	global_load_lds_dwordx4 v148, s[62:63]
	s_add_i32 m0, s64, 0x2000
	s_nop 0
	global_load_lds_dwordx4 v144, s[62:63]
	s_mov_b32 m0, s54
	s_nop 0
	global_load_lds_dwordx4 v150, s[20:21]
	s_mov_b32 m0, s55
	s_nop 0
	global_load_lds_dwordx4 v146, s[20:21]
	s_waitcnt vmcnt(8) lgkmcnt(0)
	v_mfma_f32_16x16x32_bf16 v[60:63], v[128:131], v[176:179], v[60:63]
	v_mfma_f32_16x16x32_bf16 v[56:59], v[136:139], v[176:179], v[56:59]
	v_mfma_f32_16x16x32_bf16 v[44:47], v[128:131], v[184:187], v[44:47]
	v_mfma_f32_16x16x32_bf16 v[40:43], v[136:139], v[184:187], v[40:43]
	v_mfma_f32_16x16x32_bf16 v[28:31], v[128:131], v[192:195], v[28:31]
	v_mfma_f32_16x16x32_bf16 v[24:27], v[136:139], v[192:195], v[24:27]
	v_mfma_f32_16x16x32_bf16 v[12:15], v[128:131], v[200:203], v[12:15]
	v_mfma_f32_16x16x32_bf16 v[8:11], v[136:139], v[200:203], v[8:11]
	v_mfma_f32_16x16x32_bf16 v[60:63], v[132:135], v[180:183], v[60:63]
	v_mfma_f32_16x16x32_bf16 v[56:59], v[140:143], v[180:183], v[56:59]
	v_mfma_f32_16x16x32_bf16 v[44:47], v[132:135], v[188:191], v[44:47]
	v_mfma_f32_16x16x32_bf16 v[40:43], v[140:143], v[188:191], v[40:43]
	v_mfma_f32_16x16x32_bf16 v[28:31], v[132:135], v[196:199], v[28:31]
	v_mfma_f32_16x16x32_bf16 v[24:27], v[140:143], v[196:199], v[24:27]
	v_mfma_f32_16x16x32_bf16 v[12:15], v[132:135], v[204:207], v[12:15]
	v_mfma_f32_16x16x32_bf16 v[8:11], v[140:143], v[204:207], v[8:11]
	v_mfma_f32_16x16x32_bf16 v[52:55], v[156:159], v[176:179], v[52:55]
	v_mfma_f32_16x16x32_bf16 v[48:51], v[168:171], v[176:179], v[48:51]
	v_mfma_f32_16x16x32_bf16 v[36:39], v[156:159], v[184:187], v[36:39]
	v_mfma_f32_16x16x32_bf16 v[32:35], v[168:171], v[184:187], v[32:35]
	v_mfma_f32_16x16x32_bf16 v[20:23], v[156:159], v[192:195], v[20:23]
	v_mfma_f32_16x16x32_bf16 v[16:19], v[168:171], v[192:195], v[16:19]
	v_mfma_f32_16x16x32_bf16 v[4:7], v[156:159], v[200:203], v[4:7]
	v_mfma_f32_16x16x32_bf16 v[0:3], v[168:171], v[200:203], v[0:3]
	v_mfma_f32_16x16x32_bf16 v[52:55], v[164:167], v[180:183], v[52:55]
	v_mfma_f32_16x16x32_bf16 v[48:51], v[172:175], v[180:183], v[48:51]
	v_mfma_f32_16x16x32_bf16 v[36:39], v[164:167], v[188:191], v[36:39]
	v_mfma_f32_16x16x32_bf16 v[32:35], v[172:175], v[188:191], v[32:35]
	v_mfma_f32_16x16x32_bf16 v[20:23], v[164:167], v[196:199], v[20:23]
	v_mfma_f32_16x16x32_bf16 v[16:19], v[172:175], v[196:199], v[16:19]
	v_mfma_f32_16x16x32_bf16 v[4:7], v[164:167], v[204:207], v[4:7]
	v_mfma_f32_16x16x32_bf16 v[0:3], v[172:175], v[204:207], v[0:3]
	s_barrier
	s_add_i32 s68, s68, 2
	s_add_u32 s18, s18, 0x10000
	s_addc_u32 s19, s19, 0
	s_add_u32 s66, s66, 0x10000
	s_addc_u32 s67, s67, 0
	s_cmp_gt_u32 s68, 13
	s_cbranch_scc0 .Lk0_trail
